# diff loop variant: restaging and global loads behind the first four MFMA steps (K reads still 8 deep, VALU denominators)
# speedup vs baseline: 1.0079x; 1.0079x over previous
.LBB0_147:
	s_bitcmp1_b32 s1, 0
	s_cselect_b32 s0, 0x9000, 0
	s_andn2_b32 s8, 1, s1
	v_add3_u32 v247, s0, v192, v233
	s_mul_i32 s8, s8, 0x9000
	ds_read_b128 v[156:159], v247
	ds_read_b128 v[152:155], v247 offset:128
	ds_read_b128 v[148:151], v247 offset:64
	ds_read_b128 v[144:147], v247 offset:192
	ds_read_b128 v[140:143], v247 offset:1280
	ds_read_b128 v[136:139], v247 offset:1408
	ds_read_b128 v[132:135], v247 offset:1344
	ds_read_b128 v[128:131], v247 offset:1472
	v_add_u32_e32 v160, s0, v235
	v_add3_u32 v160, v160, v236, v237
	v_xor_b32_e32 v161, 32, v238
	v_add_u32_e32 v245, v160, v161
	v_xor_b32_e32 v161, 64, v238
	v_add_u32_e32 v244, v160, v161
	v_xor_b32_e32 v161, 0x60, v238
	v_add_u32_e32 v243, v160, v161
	v_xor_b32_e32 v161, 0x80, v238
	v_add_u32_e32 v242, v160, v161
	v_xor_b32_e32 v161, 0xa0, v238
	v_add_u32_e32 v241, v160, v161
	v_xor_b32_e32 v161, 0xc0, v238
	v_add_u32_e32 v240, v160, v161
	v_xor_b32_e32 v161, 0xe0, v238
	v_add_u32_e32 v246, v160, v238
	v_add_u32_e32 v239, v160, v161
	s_waitcnt lgkmcnt(7)
	v_mfma_f32_16x16x32_bf16 v[188:191], v[156:159], v[0:3], v[40:43]
	ds_read_b128 v[156:159], v247 offset:10240
	s_waitcnt lgkmcnt(7)
	v_mfma_f32_16x16x32_bf16 v[160:163], v[152:155], v[8:11], v[44:47]
	ds_read_b128 v[152:155], v247 offset:10368
	s_waitcnt lgkmcnt(7)
	v_mfma_f32_16x16x32_bf16 v[188:191], v[148:151], v[4:7], v[188:191]
	ds_read_b128 v[148:151], v247 offset:10304
	s_waitcnt lgkmcnt(7)
	v_mfma_f32_16x16x32_bf16 v[160:163], v[144:147], v[12:15], v[160:163]
	ds_read_b128 v[144:147], v247 offset:10432
	v_add3_u32 v172, s8, v205, v207
	v_add3_u32 v173, s8, v227, v228
	s_waitcnt vmcnt(3)
	ds_write_b128 v172, v[16:19]
	v_add_u32_e32 v172, s8, v209
	s_waitcnt vmcnt(2)
	ds_write_b128 v173, v[20:23]
	v_add3_u32 v172, v172, v211, v229
	v_add_u32_e32 v173, s8, v230
	s_waitcnt vmcnt(1)
	ds_write_b128 v172, v[24:27] offset:20480
	v_add3_u32 v173, v173, v231, v232
	s_add_i32 s8, s1, 3
	s_add_i32 s0, s1, 2
	s_waitcnt vmcnt(0)
	ds_write_b128 v173, v[28:31] offset:20480
	s_min_u32 s8, s8, s83
	s_min_u32 s0, s0, s83
	s_lshl_b32 s8, s8, 6
	s_lshl_b32 s0, s0, 6
	v_add_u32_e32 v16, s8, v204
	v_add_u32_e32 v164, s8, v206
	v_add_u32_e32 v184, s0, v208
	v_add_u32_e32 v28, s0, v210
	v_ashrrev_i32_e32 v17, 31, v16
	v_ashrrev_i32_e32 v165, 31, v164
	v_ashrrev_i32_e32 v185, 31, v184
	v_ashrrev_i32_e32 v29, 31, v28
	v_lshlrev_b64 v[16:17], 11, v[16:17]
	v_lshlrev_b64 v[20:21], 11, v[164:165]
	v_lshlrev_b64 v[24:25], 11, v[184:185]
	v_lshlrev_b64 v[28:29], 11, v[28:29]
	v_lshl_add_u64 v[16:17], v[212:213], 0, v[16:17]
	v_lshl_add_u64 v[20:21], v[214:215], 0, v[20:21]
	v_lshl_add_u64 v[24:25], v[216:217], 0, v[24:25]
	v_lshl_add_u64 v[28:29], v[218:219], 0, v[28:29]
	global_load_dwordx4 v[16:19], v[16:17], off
	global_load_dwordx4 v[20:23], v[20:21], off
	global_load_dwordx4 v[24:27], v[24:25], off offset:1024
	global_load_dwordx4 v[28:31], v[28:29], off offset:1024
	s_waitcnt lgkmcnt(11)
	v_mfma_f32_16x16x32_bf16 v[184:187], v[140:143], v[0:3], v[40:43]
	ds_read_b128 v[140:143], v247 offset:11520
	s_waitcnt lgkmcnt(11)
	v_mfma_f32_16x16x32_bf16 v[168:171], v[136:139], v[8:11], v[44:47]
	ds_read_b128 v[136:139], v247 offset:11648
	s_waitcnt lgkmcnt(11)
	v_mfma_f32_16x16x32_bf16 v[184:187], v[132:135], v[4:7], v[184:187]
	ds_read_b128 v[132:135], v247 offset:11584
	s_waitcnt lgkmcnt(11)
	v_mfma_f32_16x16x32_bf16 v[168:171], v[128:131], v[12:15], v[168:171]
	ds_read_b128 v[128:131], v247 offset:11712
	s_waitcnt lgkmcnt(11)
	v_mfma_f32_16x16x32_bf16 v[180:183], v[156:159], v[0:3], v[40:43]
	ds_read_b64_tr_b16 v[156:157], v246 offset:20480
	ds_read_b64_tr_b16 v[158:159], v246 offset:21504
	s_waitcnt lgkmcnt(12)
	v_mfma_f32_16x16x32_bf16 v[164:167], v[152:155], v[8:11], v[44:47]
	ds_read_b64_tr_b16 v[152:153], v245 offset:20480
	ds_read_b64_tr_b16 v[154:155], v245 offset:21504
	s_waitcnt lgkmcnt(13)
	v_mfma_f32_16x16x32_bf16 v[180:183], v[148:151], v[4:7], v[180:183]
	ds_read_b64_tr_b16 v[148:149], v244 offset:20480
	ds_read_b64_tr_b16 v[150:151], v244 offset:21504
	s_waitcnt lgkmcnt(14)
	v_mfma_f32_16x16x32_bf16 v[164:167], v[144:147], v[12:15], v[164:167]
	ds_read_b64_tr_b16 v[144:145], v243 offset:20480
	ds_read_b64_tr_b16 v[146:147], v243 offset:21504
	s_waitcnt lgkmcnt(11)
	v_mfma_f32_16x16x32_bf16 v[172:175], v[140:143], v[0:3], v[40:43]
	ds_read_b64_tr_b16 v[140:141], v242 offset:20480
	ds_read_b64_tr_b16 v[142:143], v242 offset:21504
	s_waitcnt lgkmcnt(12)
	v_mfma_f32_16x16x32_bf16 v[176:179], v[136:139], v[8:11], v[44:47]
	ds_read_b64_tr_b16 v[136:137], v241 offset:20480
	ds_read_b64_tr_b16 v[138:139], v241 offset:21504
	s_waitcnt lgkmcnt(13)
	v_mfma_f32_16x16x32_bf16 v[172:175], v[132:135], v[4:7], v[172:175]
	ds_read_b64_tr_b16 v[132:133], v240 offset:20480
	ds_read_b64_tr_b16 v[134:135], v240 offset:21504
	s_waitcnt lgkmcnt(14)
	v_mfma_f32_16x16x32_bf16 v[176:179], v[128:131], v[12:15], v[176:179]
	ds_read_b64_tr_b16 v[128:129], v239 offset:20480
	ds_read_b64_tr_b16 v[130:131], v239 offset:21504
	s_add_i32 s8, s1, 1
	s_cmp_ge_u32 s8, s82
	s_cbranch_scc1 .LBB0_153
	s_cmp_lg_u32 s1, 0
	s_cselect_b64 s[0:1], -1, 0
	s_and_b32 s9, s8, 3
	s_cmp_lg_u32 s9, 0
	s_cselect_b64 s[14:15], -1, 0
	s_and_b64 s[0:1], s[0:1], s[14:15]
	s_and_b64 vcc, exec, s[0:1]
	s_cbranch_vccnz .LBB0_153
	v_max_f32_e32 v194, v189, v189
	v_max_f32_e32 v195, v188, v188
	v_max_f32_e32 v194, v195, v194
	v_max3_f32 v194, v194, v190, v191
	v_max3_f32 v194, v194, v184, v185
	v_max3_f32 v194, v194, v186, v187
	v_max3_f32 v194, v194, v180, v181
	v_max3_f32 v194, v194, v182, v183
	v_max3_f32 v194, v194, v172, v173
	v_max3_f32 v194, v194, v174, v175
	v_mov_b32_e32 v195, v194
	s_nop 1
	v_permlane16_swap_b32_e32 v194, v195
	v_max_f32_e32 v195, v195, v195
	v_max_f32_e32 v194, v194, v194
	v_max_f32_e32 v194, v194, v195
	v_mov_b32_e32 v195, v194
	s_nop 1
	v_permlane32_swap_b32_e32 v194, v195
	v_max_f32_e32 v195, v195, v195
	v_max_f32_e32 v194, v194, v194
	v_max_f32_e32 v247, v194, v195
	v_cmp_lt_f32_e32 vcc, s44, v247
	s_cbranch_vccz .LBB0_151
	s_nop 0
	v_cndmask_b32_e32 v247, 0, v247, vcc
	v_exp_f32_e64 v194, -v247
	v_lshlrev_b32_e32 v196, 16, v72
	v_and_b32_e32 v197, 0xffff0000, v72
	v_sub_f32_e32 v191, v191, v247
	v_pk_mul_f32 v[196:197], v[194:195], v[196:197] op_sel_hi:[0,1]
	v_cvt_pk_bf16_f32 v72, v196, v197
	v_lshlrev_b32_e32 v196, 16, v73
	v_and_b32_e32 v197, 0xffff0000, v73
	v_pk_mul_f32 v[196:197], v[194:195], v[196:197] op_sel_hi:[0,1]
	v_cvt_pk_bf16_f32 v73, v196, v197
	v_lshlrev_b32_e32 v196, 16, v74
	v_and_b32_e32 v197, 0xffff0000, v74
	v_pk_mul_f32 v[196:197], v[194:195], v[196:197] op_sel_hi:[0,1]
	v_cvt_pk_bf16_f32 v74, v196, v197
	v_lshlrev_b32_e32 v196, 16, v75
	v_and_b32_e32 v197, 0xffff0000, v75
	v_pk_mul_f32 v[196:197], v[194:195], v[196:197] op_sel_hi:[0,1]
	v_cvt_pk_bf16_f32 v75, v196, v197
	v_lshlrev_b32_e32 v196, 16, v56
	v_and_b32_e32 v197, 0xffff0000, v56
	v_pk_mul_f32 v[196:197], v[194:195], v[196:197] op_sel_hi:[0,1]
	v_cvt_pk_bf16_f32 v56, v196, v197
	v_lshlrev_b32_e32 v196, 16, v57
	v_and_b32_e32 v197, 0xffff0000, v57
	v_pk_mul_f32 v[196:197], v[194:195], v[196:197] op_sel_hi:[0,1]
	v_cvt_pk_bf16_f32 v57, v196, v197
	v_lshlrev_b32_e32 v196, 16, v58
	v_and_b32_e32 v197, 0xffff0000, v58
	v_pk_mul_f32 v[196:197], v[194:195], v[196:197] op_sel_hi:[0,1]
	v_cvt_pk_bf16_f32 v58, v196, v197
	v_lshlrev_b32_e32 v196, 16, v59
	v_and_b32_e32 v197, 0xffff0000, v59
	v_pk_mul_f32 v[110:111], v[110:111], v[194:195] op_sel_hi:[1,0]
	v_pk_mul_f32 v[108:109], v[108:109], v[194:195] op_sel_hi:[1,0]
	v_pk_mul_f32 v[122:123], v[122:123], v[194:195] op_sel_hi:[1,0]
	v_pk_mul_f32 v[120:121], v[120:121], v[194:195] op_sel_hi:[1,0]
	v_pk_mul_f32 v[114:115], v[114:115], v[194:195] op_sel_hi:[1,0]
	v_pk_mul_f32 v[112:113], v[112:113], v[194:195] op_sel_hi:[1,0]
	v_pk_mul_f32 v[98:99], v[98:99], v[194:195] op_sel_hi:[1,0]
	v_pk_mul_f32 v[96:97], v[96:97], v[194:195] op_sel_hi:[1,0]
	v_pk_mul_f32 v[86:87], v[86:87], v[194:195] op_sel_hi:[1,0]
	v_pk_mul_f32 v[84:85], v[84:85], v[194:195] op_sel_hi:[1,0]
	v_pk_mul_f32 v[70:71], v[70:71], v[194:195] op_sel_hi:[1,0]
	v_pk_mul_f32 v[68:69], v[68:69], v[194:195] op_sel_hi:[1,0]
	v_pk_mul_f32 v[62:63], v[62:63], v[194:195] op_sel_hi:[1,0]
	v_pk_mul_f32 v[60:61], v[60:61], v[194:195] op_sel_hi:[1,0]
	v_pk_mul_f32 v[50:51], v[50:51], v[194:195] op_sel_hi:[1,0]
	v_pk_mul_f32 v[48:49], v[48:49], v[194:195] op_sel_hi:[1,0]
	v_pk_mul_f32 v[34:35], v[34:35], v[194:195] op_sel_hi:[1,0]
	v_pk_mul_f32 v[32:33], v[32:33], v[194:195] op_sel_hi:[1,0]
	v_pk_mul_f32 v[194:195], v[194:195], v[196:197] op_sel_hi:[0,1]
	v_sub_f32_e32 v190, v190, v247
	v_sub_f32_e32 v189, v189, v247
	v_sub_f32_e32 v188, v188, v247
	v_sub_f32_e32 v187, v187, v247
	v_sub_f32_e32 v186, v186, v247
	v_sub_f32_e32 v185, v185, v247
	v_sub_f32_e32 v184, v184, v247
	v_sub_f32_e32 v183, v183, v247
	v_sub_f32_e32 v182, v182, v247
	v_sub_f32_e32 v181, v181, v247
	v_sub_f32_e32 v180, v180, v247
	v_sub_f32_e32 v175, v175, v247
	v_sub_f32_e32 v174, v174, v247
	v_sub_f32_e32 v173, v173, v247
	v_sub_f32_e32 v172, v172, v247
	v_cvt_pk_bf16_f32 v59, v194, v195
	v_sub_f32_e32 v43, v43, v247
	v_sub_f32_e32 v42, v42, v247
	v_sub_f32_e32 v41, v41, v247
	v_sub_f32_e32 v40, v40, v247
